# phase_up unit prologue: K-tile 1 LDS-DMA issued before the wait for K-tile 0 (two DMA round trips overlap)
# speedup vs baseline: 1.0011x; 1.0011x over previous
.LBB0_917:
	v_mov_b32_e32 v139, v5
	s_movk_i32 s70, 0xa00
	s_movk_i32 s71, 0x50
	v_lshrrev_b32_e32 v186, 6, v5
	v_and_b32_e32 v187, 31, v5
	v_bfe_u32 v188, v5, 5, 1
	v_lshlrev_b32_e32 v188, 3, v188
	v_mad_u32_u24 v182, v186, s70, v188
	v_mad_u32_u24 v182, v187, s71, v182
	v_add_u32_e32 v182, 32, v182
	v_and_b32_e32 v187, 63, v5
	v_lshrrev_b32_e32 v188, 2, v187
	v_and_b32_e32 v187, 3, v187
	v_lshlrev_b32_e32 v187, 4, v187
	v_mad_u32_u24 v183, v186, s70, v187
	v_mad_u32_u24 v183, v188, s71, v183
	v_add_u32_e32 v183, 32, v183
	v_lshl_add_u32 v185, v188, 7, v187
	s_movk_i32 s70, 0xc0
	v_mad_u32_u24 v184, v188, s70, v187
	s_cmpk_gt_i32 s12, 0xbf
	s_mov_b64 s[0:1], -1
	s_cbranch_scc0 .LBB0_967
	s_add_i32 s0, s12, 0xffffff40
	v_ashrrev_i32_e32 v1, 6, v139
	v_bfe_u32 v0, v139, 3, 3
	s_lshr_b32 s68, s0, 2
	v_lshl_or_b32 v0, v1, 3, v0
	s_and_b32 s13, s12, 3
	s_lshl_b64 s[0:1], s[68:69], 16
	v_readlane_b32 s4, v254, 27
	v_lshlrev_b32_e32 v20, 10, v1
	v_lshrrev_b32_e32 v1, 1, v0
	v_readlane_b32 s5, v254, 28
	s_add_u32 s0, s4, s0
	v_xor_b32_e32 v6, v1, v139
	v_ashrrev_i32_e32 v1, 31, v0
	s_addc_u32 s1, s5, s1
	v_add_u32_e32 v21, 32, v20
	v_lshlrev_b64 v[0:1], 8, v[0:1]
	v_lshlrev_b32_e32 v6, 4, v6
	s_lshl_b32 s4, s13, 16
	v_lshl_add_u64 v[2:3], s[0:1], 0, v[0:1]
	v_and_b32_e32 v6, 0x70, v6
	v_mov_b32_e32 v7, v4
	v_readfirstlane_b32 s6, v21
	v_add_u32_e32 v10, 0x8000, v21
	s_add_u32 s4, s10, s4
	v_lshl_add_u64 v[2:3], v[2:3], 0, v[6:7]
	s_mov_b32 m0, s6
	v_readfirstlane_b32 s6, v10
	s_addc_u32 s5, s11, 0
	global_load_lds_dwordx4 v[2:3], off
	s_mov_b32 m0, s6
	s_mov_b64 s[6:7], 0x4000
	v_lshl_add_u64 v[8:9], s[4:5], 0, v[0:1]
	v_add_u32_e32 v14, 0x2000, v21
	v_lshl_add_u64 v[10:11], v[0:1], 0, s[6:7]
	v_lshl_add_u64 v[8:9], v[8:9], 0, v[6:7]
	v_lshl_add_u64 v[12:13], s[0:1], 0, v[10:11]
	v_readfirstlane_b32 s6, v14
	v_add_u32_e32 v14, 0xa000, v21
	global_load_lds_dwordx4 v[8:9], off
	v_lshl_add_u64 v[12:13], v[12:13], 0, v[6:7]
	s_mov_b32 m0, s6
	v_readfirstlane_b32 s6, v14
	global_load_lds_dwordx4 v[12:13], off
	s_mov_b32 m0, s6
	s_mov_b64 s[6:7], 0x8000
	v_lshl_add_u64 v[10:11], s[4:5], 0, v[10:11]
	v_add_u32_e32 v18, 0x4000, v21
	v_lshl_add_u64 v[14:15], v[0:1], 0, s[6:7]
	v_lshl_add_u64 v[10:11], v[10:11], 0, v[6:7]
	v_lshl_add_u64 v[16:17], s[0:1], 0, v[14:15]
	v_readfirstlane_b32 s6, v18
	v_add_u32_e32 v18, 0xc000, v21
	global_load_lds_dwordx4 v[10:11], off
	v_lshl_add_u64 v[16:17], v[16:17], 0, v[6:7]
	s_mov_b32 m0, s6
	v_readfirstlane_b32 s6, v18
	global_load_lds_dwordx4 v[16:17], off
	s_mov_b32 m0, s6
	s_mov_b64 s[6:7], 0xc000
	v_lshl_add_u64 v[0:1], v[0:1], 0, s[6:7]
	v_lshl_add_u64 v[14:15], s[4:5], 0, v[14:15]
	v_add_u32_e32 v22, 0x6000, v21
	v_lshl_add_u64 v[18:19], s[0:1], 0, v[0:1]
	v_lshl_add_u64 v[0:1], s[4:5], 0, v[0:1]
	v_lshl_add_u64 v[14:15], v[14:15], 0, v[6:7]
	v_lshl_add_u64 v[18:19], v[18:19], 0, v[6:7]
	v_readfirstlane_b32 s0, v22
	v_lshl_add_u64 v[0:1], v[0:1], 0, v[6:7]
	v_add_u32_e32 v6, 0xe000, v21
	global_load_lds_dwordx4 v[14:15], off
	s_mov_b32 m0, s0
	v_readfirstlane_b32 s0, v6
	v_lshrrev_b32_e32 v6, 5, v139
	v_bfe_u32 v148, v139, 1, 3
	v_bitop3_b32 v6, v6, v148, 1 bitop3:0x6c
	global_load_lds_dwordx4 v[18:19], off
	s_mov_b32 m0, s0
	v_lshlrev_b32_e32 v149, 4, v6
	v_lshlrev_b32_e32 v6, 7, v139
	s_add_i32 s0, 32, 0x10000
	v_and_b32_e32 v150, 0x6f80, v6
	v_add_u32_e32 v6, s0, v20
	global_load_lds_dwordx4 v[0:1], off
	v_readfirstlane_b32 s1, v6
	v_lshl_add_u64 v[2:3], v[2:3], 0, s[54:55]
	s_mov_b32 m0, s1
	global_load_lds_dwordx4 v[2:3], off
	v_lshl_add_u64 v[2:3], v[8:9], 0, s[54:55]
	v_add_u32_e32 v8, 0x8000, v6
	v_and_b32_e32 v152, 31, v139
	v_readfirstlane_b32 s1, v8
	v_add_u32_e32 v8, 0x2000, v6
	s_mov_b32 m0, s1
	v_readfirstlane_b32 s1, v8
	v_add_u32_e32 v8, 0xa000, v6
	global_load_lds_dwordx4 v[2:3], off
	v_lshl_add_u64 v[2:3], v[12:13], 0, s[54:55]
	s_mov_b32 m0, s1
	v_readfirstlane_b32 s1, v8
	v_add_u32_e32 v8, 0x4000, v6
	global_load_lds_dwordx4 v[2:3], off
	v_lshl_add_u64 v[2:3], v[10:11], 0, s[54:55]
	s_mov_b32 m0, s1
	v_readfirstlane_b32 s1, v8
	v_add_u32_e32 v8, 0xc000, v6
	global_load_lds_dwordx4 v[2:3], off
	v_lshl_add_u64 v[2:3], v[16:17], 0, s[54:55]
	s_mov_b32 m0, s1
	v_readfirstlane_b32 s1, v8
	v_add_u32_e32 v8, 0x6000, v6
	global_load_lds_dwordx4 v[2:3], off
	v_lshl_add_u64 v[2:3], v[14:15], 0, s[54:55]
	s_mov_b32 m0, s1
	v_readfirstlane_b32 s1, v8
	global_load_lds_dwordx4 v[2:3], off
	v_lshl_add_u64 v[2:3], v[18:19], 0, s[54:55]
	s_mov_b32 m0, s1
	v_lshrrev_b32_e32 v7, 1, v139
	global_load_lds_dwordx4 v[2:3], off
	v_add_u32_e32 v2, 0xe000, v6
	v_lshl_add_u64 v[0:1], v[0:1], 0, s[54:55]
	v_readfirstlane_b32 s1, v2
	s_mov_b32 m0, s1
	s_mov_b32 s1, 0x1ffff80
	v_and_or_b32 v7, v7, s1, v152
	v_add_u32_e32 v6, 32, v149
	v_lshlrev_b32_e32 v151, 7, v7
	global_load_lds_dwordx4 v[0:1], off
	v_add_u32_e32 v10, v6, v150
	v_add_u32_e32 v14, v6, v151
	s_waitcnt vmcnt(8)
	s_waitcnt lgkmcnt(0)
	s_barrier
	ds_read_b128 v[0:3], v10 offset:32768
	ds_read_b128 v[6:9], v14
	ds_read_b128 v[10:13], v10 offset:36864
	s_waitcnt lgkmcnt(0)
	v_mfma_f32_32x32x16_bf16 v[118:133], v[0:3], v[6:9], 0
	v_bfe_u32 v153, v139, 5, 1
	s_add_i32 s1, 32, 0x18000
	v_mfma_f32_32x32x16_bf16 v[102:117], v[10:13], v[6:9], 0
	ds_read_b128 v[6:9], v14 offset:4096
	s_waitcnt lgkmcnt(0)
	v_mfma_f32_32x32x16_bf16 v[86:101], v[0:3], v[6:9], 0
	v_mfma_f32_32x32x16_bf16 v[70:85], v[10:13], v[6:9], 0
	ds_read_b128 v[6:9], v14 offset:8192
	s_waitcnt lgkmcnt(0)
	v_mfma_f32_32x32x16_bf16 v[54:69], v[0:3], v[6:9], 0
	v_mfma_f32_32x32x16_bf16 v[38:53], v[10:13], v[6:9], 0
	ds_read_b128 v[6:9], v14 offset:12288
	s_waitcnt lgkmcnt(0)
	v_mfma_f32_32x32x16_bf16 v[22:37], v[0:3], v[6:9], 0
	v_bitop3_b32 v0, v153, v148, 2 bitop3:0x36
	v_lshlrev_b32_e32 v154, 4, v0
	v_add_u32_e32 v134, 32, v154
	v_add_u32_e32 v144, v134, v150
	v_add_u32_e32 v155, v134, v151
	ds_read_b128 v[0:3], v144 offset:32768
	ds_read_b128 v[134:137], v155
	ds_read_b128 v[144:147], v144 offset:36864
	s_waitcnt lgkmcnt(0)
	v_mfma_f32_32x32x16_bf16 v[118:133], v[0:3], v[134:137], v[118:133]
	v_mfma_f32_32x32x16_bf16 v[102:117], v[144:147], v[134:137], v[102:117]
	ds_read_b128 v[134:137], v155 offset:4096
	s_waitcnt lgkmcnt(0)
	v_mfma_f32_32x32x16_bf16 v[86:101], v[0:3], v[134:137], v[86:101]
	v_mfma_f32_32x32x16_bf16 v[70:85], v[144:147], v[134:137], v[70:85]
	ds_read_b128 v[134:137], v155 offset:8192
	v_mfma_f32_32x32x16_bf16 v[6:21], v[10:13], v[6:9], 0
	s_waitcnt lgkmcnt(0)
	v_mfma_f32_32x32x16_bf16 v[54:69], v[0:3], v[134:137], v[54:69]
	v_mfma_f32_32x32x16_bf16 v[38:53], v[144:147], v[134:137], v[38:53]
	ds_read_b128 v[134:137], v155 offset:12288
	s_waitcnt lgkmcnt(0)
	v_mfma_f32_32x32x16_bf16 v[22:37], v[0:3], v[134:137], v[22:37]
	v_bitop3_b32 v0, v153, v148, 4 bitop3:0x36
	v_lshlrev_b32_e32 v155, 4, v0
	v_mfma_f32_32x32x16_bf16 v[6:21], v[144:147], v[134:137], v[6:21]
	v_add_u32_e32 v134, 32, v155
	v_add_u32_e32 v144, v134, v150
	v_add_u32_e32 v156, v134, v151
	ds_read_b128 v[0:3], v144 offset:32768
	ds_read_b128 v[134:137], v156
	ds_read_b128 v[144:147], v144 offset:36864
	s_waitcnt lgkmcnt(0)
	v_mfma_f32_32x32x16_bf16 v[118:133], v[0:3], v[134:137], v[118:133]
	v_mfma_f32_32x32x16_bf16 v[102:117], v[144:147], v[134:137], v[102:117]
	ds_read_b128 v[134:137], v156 offset:4096
	s_waitcnt lgkmcnt(0)
	v_mfma_f32_32x32x16_bf16 v[86:101], v[0:3], v[134:137], v[86:101]
	v_mfma_f32_32x32x16_bf16 v[70:85], v[144:147], v[134:137], v[70:85]
	ds_read_b128 v[134:137], v156 offset:8192
	s_waitcnt lgkmcnt(0)
	v_mfma_f32_32x32x16_bf16 v[54:69], v[0:3], v[134:137], v[54:69]
	v_mfma_f32_32x32x16_bf16 v[38:53], v[144:147], v[134:137], v[38:53]
	ds_read_b128 v[134:137], v156 offset:12288
	s_waitcnt lgkmcnt(0)
	v_mfma_f32_32x32x16_bf16 v[22:37], v[0:3], v[134:137], v[22:37]
	v_bitop3_b32 v0, v153, v148, 6 bitop3:0x36
	v_lshlrev_b32_e32 v148, 4, v0
	v_mfma_f32_32x32x16_bf16 v[6:21], v[144:147], v[134:137], v[6:21]
	v_add_u32_e32 v134, 32, v148
	v_add_u32_e32 v144, v134, v150
	v_add_u32_e32 v153, v134, v151
	ds_read_b128 v[0:3], v144 offset:32768
	ds_read_b128 v[134:137], v153
	ds_read_b128 v[144:147], v144 offset:36864
	s_waitcnt lgkmcnt(0)
	v_mfma_f32_32x32x16_bf16 v[118:133], v[0:3], v[134:137], v[118:133]
	v_mfma_f32_32x32x16_bf16 v[102:117], v[144:147], v[134:137], v[102:117]
	ds_read_b128 v[134:137], v153 offset:4096
	s_waitcnt lgkmcnt(0)
	v_mfma_f32_32x32x16_bf16 v[86:101], v[0:3], v[134:137], v[86:101]
	v_mfma_f32_32x32x16_bf16 v[70:85], v[144:147], v[134:137], v[70:85]
	ds_read_b128 v[134:137], v153 offset:8192
	s_waitcnt lgkmcnt(0)
	v_mfma_f32_32x32x16_bf16 v[54:69], v[0:3], v[134:137], v[54:69]
	v_mfma_f32_32x32x16_bf16 v[38:53], v[144:147], v[134:137], v[38:53]
	ds_read_b128 v[134:137], v153 offset:12288
	s_waitcnt vmcnt(0)
	s_waitcnt vmcnt(0) lgkmcnt(0)
	s_barrier
	v_mfma_f32_32x32x16_bf16 v[6:21], v[144:147], v[134:137], v[6:21]
	v_add3_u32 v144, s1, v149, v150
	v_add3_u32 v149, s0, v149, v151
	v_mfma_f32_32x32x16_bf16 v[22:37], v[0:3], v[134:137], v[22:37]
	ds_read_b128 v[0:3], v144
	ds_read_b128 v[134:137], v149
	ds_read_b128 v[144:147], v144 offset:4096
	s_waitcnt lgkmcnt(1)
	v_mfma_f32_32x32x16_bf16 v[118:133], v[0:3], v[134:137], v[118:133]
	s_waitcnt lgkmcnt(0)
	v_mfma_f32_32x32x16_bf16 v[102:117], v[144:147], v[134:137], v[102:117]
	ds_read_b128 v[134:137], v149 offset:4096
	s_waitcnt lgkmcnt(0)
	v_mfma_f32_32x32x16_bf16 v[86:101], v[0:3], v[134:137], v[86:101]
	v_mfma_f32_32x32x16_bf16 v[70:85], v[144:147], v[134:137], v[70:85]
	ds_read_b128 v[134:137], v149 offset:8192
	s_waitcnt lgkmcnt(0)
	v_mfma_f32_32x32x16_bf16 v[54:69], v[0:3], v[134:137], v[54:69]
	v_mfma_f32_32x32x16_bf16 v[38:53], v[144:147], v[134:137], v[38:53]
	ds_read_b128 v[134:137], v149 offset:12288
	v_add3_u32 v149, s0, v154, v151
	s_waitcnt lgkmcnt(0)
	v_mfma_f32_32x32x16_bf16 v[6:21], v[144:147], v[134:137], v[6:21]
	v_add3_u32 v144, s1, v154, v150
	v_mfma_f32_32x32x16_bf16 v[22:37], v[0:3], v[134:137], v[22:37]
	ds_read_b128 v[0:3], v144
	ds_read_b128 v[134:137], v149
	ds_read_b128 v[144:147], v144 offset:4096
	s_waitcnt lgkmcnt(1)
	v_mfma_f32_32x32x16_bf16 v[118:133], v[0:3], v[134:137], v[118:133]
	s_waitcnt lgkmcnt(0)
	v_mfma_f32_32x32x16_bf16 v[102:117], v[144:147], v[134:137], v[102:117]
	ds_read_b128 v[134:137], v149 offset:4096
	s_waitcnt lgkmcnt(0)
	v_mfma_f32_32x32x16_bf16 v[86:101], v[0:3], v[134:137], v[86:101]
	v_mfma_f32_32x32x16_bf16 v[70:85], v[144:147], v[134:137], v[70:85]
	ds_read_b128 v[134:137], v149 offset:8192
	s_waitcnt lgkmcnt(0)
	v_mfma_f32_32x32x16_bf16 v[54:69], v[0:3], v[134:137], v[54:69]
	v_mfma_f32_32x32x16_bf16 v[38:53], v[144:147], v[134:137], v[38:53]
	ds_read_b128 v[134:137], v149 offset:12288
	v_add3_u32 v149, s0, v155, v151
	s_waitcnt lgkmcnt(0)
	v_mfma_f32_32x32x16_bf16 v[6:21], v[144:147], v[134:137], v[6:21]
	v_add3_u32 v144, s1, v155, v150
	v_mfma_f32_32x32x16_bf16 v[22:37], v[0:3], v[134:137], v[22:37]
	ds_read_b128 v[0:3], v144
	ds_read_b128 v[134:137], v149
	ds_read_b128 v[144:147], v144 offset:4096
	s_waitcnt lgkmcnt(1)
	v_mfma_f32_32x32x16_bf16 v[118:133], v[0:3], v[134:137], v[118:133]
	s_waitcnt lgkmcnt(0)
	v_mfma_f32_32x32x16_bf16 v[102:117], v[144:147], v[134:137], v[102:117]
	ds_read_b128 v[134:137], v149 offset:4096
	s_waitcnt lgkmcnt(0)
	v_mfma_f32_32x32x16_bf16 v[86:101], v[0:3], v[134:137], v[86:101]
	v_mfma_f32_32x32x16_bf16 v[70:85], v[144:147], v[134:137], v[70:85]
	ds_read_b128 v[134:137], v149 offset:8192
	s_waitcnt lgkmcnt(0)
	v_mfma_f32_32x32x16_bf16 v[54:69], v[0:3], v[134:137], v[54:69]
	v_mfma_f32_32x32x16_bf16 v[38:53], v[144:147], v[134:137], v[38:53]
	ds_read_b128 v[134:137], v149 offset:12288
	s_waitcnt lgkmcnt(0)
	v_mfma_f32_32x32x16_bf16 v[6:21], v[144:147], v[134:137], v[6:21]
	v_add3_u32 v144, s1, v148, v150
	ds_read_b128 v[154:157], v144 offset:4096
	v_add3_u32 v145, s0, v148, v151
	s_movk_i32 s0, 0x9f
	v_mfma_f32_32x32x16_bf16 v[22:37], v[0:3], v[134:137], v[22:37]
	ds_read_b128 v[0:3], v144
	ds_read_b128 v[134:137], v145
	s_waitcnt lgkmcnt(0)
	v_mfma_f32_32x32x16_bf16 v[118:133], v[0:3], v[134:137], v[118:133]
	v_mfma_f32_32x32x16_bf16 v[102:117], v[154:157], v[134:137], v[102:117]
	ds_read_b128 v[134:137], v145 offset:4096
	ds_read_b128 v[148:151], v145 offset:8192
	ds_read_b128 v[158:161], v145 offset:12288
	s_waitcnt vmcnt(0)
	s_waitcnt lgkmcnt(0)
	s_barrier
	v_mfma_f32_32x32x16_bf16 v[86:101], v[0:3], v[134:137], v[86:101]
	v_mfma_f32_32x32x16_bf16 v[70:85], v[154:157], v[134:137], v[70:85]
	v_ashrrev_i32_e32 v134, 1, v139
	v_and_b32_e32 v134, 0xffffff80, v134
	v_or_b32_e32 v135, v134, v152
	v_lshl_add_u32 v144, s68, 8, v135
	v_bitop3_b32 v146, v134, s0, v152 bitop3:0xc8
	v_subrev_co_u32_e32 v134, vcc, 0x4000, v144
	v_mfma_f32_32x32x16_bf16 v[54:69], v[0:3], v[148:151], v[54:69]
	v_lshrrev_b32_e32 v137, 9, v134
	v_and_b32_e32 v134, 0x19f, v144
	v_ashrrev_i32_e32 v136, 8, v144
	s_mov_b64 s[4:5], vcc
	v_cmp_lt_i32_e64 s[6:7], s89, v144
	v_mov_b32_e32 v152, v146
	v_mov_b32_e32 v145, v136
	v_mfma_f32_32x32x16_bf16 v[38:53], v[154:157], v[148:151], v[38:53]
	v_or_b32_e32 v149, 0x1000, v134
	v_add_u32_e32 v134, 0xffffe000, v144
	v_lshrrev_b32_e32 v150, 12, v134
	v_and_b32_e32 v151, 0xf9f, v144
	v_mov_b64_e32 v[134:135], 0xc952000
	v_cndmask_b32_e64 v147, v149, v151, s[4:5]
	v_cndmask_b32_e64 v148, v137, v150, s[4:5]
	v_mfma_f32_32x32x16_bf16 v[22:37], v[0:3], v[158:161], v[22:37]
	v_mov_b64_e32 v[2:3], 0x100
	v_mov_b64_e32 v[0:1], 0xdb62000
	v_mfma_f32_32x32x16_bf16 v[6:21], v[154:157], v[158:161], v[6:21]
	s_and_saveexec_b64 s[0:1], s[6:7]
	v_cndmask_b32_e64 v152, v149, v151, s[4:5]
	v_cndmask_b32_e64 v145, v137, v150, s[4:5]
	v_mov_b64_e32 v[2:3], 0x1200
	v_mov_b64_e32 v[134:135], 0xd152000
	v_mov_b64_e32 v[0:1], 0xe362000
	s_or_b64 exec, exec, s[0:1]
	v_lshrrev_b32_e32 v3, 3, v139
	v_and_b32_e32 v137, 0x80, v139
	v_lshl_or_b32 v137, s13, 8, v137
	v_and_b32_e32 v151, 4, v3
	v_or_b32_e32 v149, 0xffffffc0, v151
	v_lshrrev_b32_e32 v137, 7, v137
	v_and_b32_e32 v150, 64, v139
	v_lshl_or_b32 v3, v145, 3, v137
	v_cmp_ne_u32_e32 vcc, 0, v150
	v_add_u32_e32 v145, v149, v150
	s_and_saveexec_b64 s[0:1], vcc
	s_xor_b64 s[0:1], exec, s[0:1]
	s_cbranch_execz .LBB0_922
	v_mad_i64_i32 v[134:135], s[14:15], v2, v3, 0
	v_lshl_add_u64 v[0:1], s[26:27], 0, v[0:1]
	v_lshlrev_b64 v[134:135], 7, v[134:135]
	v_lshl_add_u64 v[0:1], v[0:1], 0, v[134:135]
	v_mad_u64_u32 v[134:135], s[14:15], v2, v145, 0
	v_lshl_add_u64 v[0:1], v[134:135], 1, v[0:1]
	v_lshlrev_b32_e32 v134, 1, v152
	v_mov_b32_e32 v135, v4
	v_lshl_add_u64 v[0:1], v[0:1], 0, v[134:135]
	v_cvt_pk_bf16_f32 v3, v118, s0
	global_store_short v[0:1], v3, off
	v_cvt_pk_bf16_f32 v3, v119, s0
	v_lshlrev_b32_e32 v118, 1, v2
	v_mov_b32_e32 v119, v4
	v_lshl_add_u64 v[0:1], v[0:1], 0, v[118:119]
	global_store_short v[0:1], v3, off
	v_cvt_pk_bf16_f32 v3, v120, s0
	v_lshl_add_u64 v[0:1], v[0:1], 0, v[118:119]
	global_store_short v[0:1], v3, off
	v_cvt_pk_bf16_f32 v3, v121, s0
	v_lshl_add_u64 v[0:1], v[0:1], 0, v[118:119]
	global_store_short v[0:1], v3, off
	v_cvt_pk_bf16_f32 v3, v122, s0
	v_mad_u64_u32 v[0:1], s[14:15], v2, 10, v[0:1]
	global_store_short v[0:1], v3, off
	v_cvt_pk_bf16_f32 v3, v123, s0
	v_lshl_add_u64 v[0:1], v[0:1], 0, v[118:119]
	global_store_short v[0:1], v3, off
	v_cvt_pk_bf16_f32 v3, v124, s0
	v_lshl_add_u64 v[0:1], v[0:1], 0, v[118:119]
	global_store_short v[0:1], v3, off
	v_cvt_pk_bf16_f32 v3, v125, s0
	v_lshl_add_u64 v[0:1], v[0:1], 0, v[118:119]
	global_store_short v[0:1], v3, off
	v_cvt_pk_bf16_f32 v3, v126, s0
	v_mad_u64_u32 v[0:1], s[14:15], v2, 10, v[0:1]
	global_store_short v[0:1], v3, off
	v_cvt_pk_bf16_f32 v3, v127, s0
	v_lshl_add_u64 v[0:1], v[0:1], 0, v[118:119]
	global_store_short v[0:1], v3, off
	v_cvt_pk_bf16_f32 v3, v128, s0
	v_lshl_add_u64 v[0:1], v[0:1], 0, v[118:119]
	global_store_short v[0:1], v3, off
	v_cvt_pk_bf16_f32 v3, v129, s0
	v_lshl_add_u64 v[0:1], v[0:1], 0, v[118:119]
	global_store_short v[0:1], v3, off
	v_cvt_pk_bf16_f32 v3, v130, s0
	v_mad_u64_u32 v[0:1], s[14:15], v2, 10, v[0:1]
	global_store_short v[0:1], v3, off
	v_cvt_pk_bf16_f32 v2, v131, s0
	v_lshl_add_u64 v[0:1], v[0:1], 0, v[118:119]
	global_store_short v[0:1], v2, off
	v_cvt_pk_bf16_f32 v2, v132, s0
	v_lshl_add_u64 v[0:1], v[0:1], 0, v[118:119]
	global_store_short v[0:1], v2, off
	v_cvt_pk_bf16_f32 v2, v133, s0
	v_lshl_add_u64 v[0:1], v[0:1], 0, v[118:119]
	global_store_short v[0:1], v2, off

.LBB0_967:
	s_and_b64 vcc, exec, s[0:1]
	s_cbranch_vccz .LBB0_916
	s_mul_hi_i32 s0, s12, 0x2aaaaaab
	s_lshr_b32 s1, s0, 31
	s_ashr_i32 s0, s0, 2
	s_add_i32 s0, s0, s1
	s_lshl_b32 s1, s0, 3
	s_and_b32 s4, s12, 7
	s_mulk_i32 s0, 0xffe8
	s_or_b32 s4, s1, s4
	s_add_i32 s0, s12, s0
	s_ashr_i32 s5, s4, 31
	s_ashr_i32 s0, s0, 3
	s_lshl_b64 s[6:7], s[4:5], 17
	v_readlane_b32 s14, v254, 29
	v_ashrrev_i32_e32 v1, 6, v139
	v_bfe_u32 v0, v139, 3, 3
	v_readlane_b32 s15, v254, 30
	s_add_u32 s6, s14, s6
	v_lshl_or_b32 v0, v1, 3, v0
	s_addc_u32 s7, s15, s7
	s_ashr_i32 s1, s0, 31
	v_lshlrev_b32_e32 v14, 10, v1
	v_lshrrev_b32_e32 v1, 1, v0
	s_lshl_b64 s[14:15], s[0:1], 17
	v_xor_b32_e32 v2, v1, v139
	v_add_u32_e32 v15, 32, v14
	v_ashrrev_i32_e32 v1, 31, v0
	s_add_u32 s14, s8, s14
	v_lshlrev_b64 v[6:7], 9, v[0:1]
	v_add_u32_e32 v10, 0x8000, v15
	s_mov_b64 s[16:17], 0x8000
	s_addc_u32 s15, s9, s15
	v_lshlrev_b32_e32 v2, 4, v2
	v_readfirstlane_b32 s19, v10
	v_lshl_add_u64 v[10:11], v[6:7], 0, s[16:17]
	v_and_b32_e32 v8, 0x70, v2
	v_mov_b32_e32 v9, v4
	v_lshl_add_u64 v[12:13], s[6:7], 0, v[10:11]
	v_lshl_add_u64 v[10:11], s[14:15], 0, v[10:11]
	v_lshl_add_u64 v[0:1], s[6:7], 0, v[6:7]
	v_readfirstlane_b32 s18, v15
	v_lshl_add_u64 v[136:137], v[10:11], 0, v[8:9]
	v_add_u32_e32 v10, 0xa000, v15
	s_mov_b64 s[16:17], 0x10000
	v_lshl_add_u64 v[0:1], v[0:1], 0, v[8:9]
	s_mov_b32 m0, s18
	v_lshl_add_u64 v[2:3], s[14:15], 0, v[6:7]
	v_add_u32_e32 v16, 0x2000, v15
	v_readfirstlane_b32 s21, v10
	v_lshl_add_u64 v[10:11], v[6:7], 0, s[16:17]
	global_load_lds_dwordx4 v[0:1], off
	v_lshl_add_u64 v[2:3], v[2:3], 0, v[8:9]
	s_mov_b32 m0, s19
	v_lshl_add_u64 v[134:135], v[12:13], 0, v[8:9]
	v_readfirstlane_b32 s20, v16
	v_lshl_add_u64 v[12:13], s[6:7], 0, v[10:11]
	v_lshl_add_u64 v[10:11], s[14:15], 0, v[10:11]
	s_mov_b64 s[16:17], 0x18000
	global_load_lds_dwordx4 v[2:3], off
	s_mov_b32 m0, s20
	v_add_u32_e32 v16, 0x4000, v15
	v_lshl_add_u64 v[146:147], v[10:11], 0, v[8:9]
	v_add_u32_e32 v10, 0xc000, v15
	v_lshl_add_u64 v[6:7], v[6:7], 0, s[16:17]
	global_load_lds_dwordx4 v[134:135], off
	s_mov_b32 m0, s21
	v_readfirstlane_b32 s22, v16
	v_readfirstlane_b32 s23, v10
	v_lshl_add_u64 v[10:11], s[6:7], 0, v[6:7]
	v_lshl_add_u64 v[6:7], s[14:15], 0, v[6:7]
	global_load_lds_dwordx4 v[136:137], off
	v_lshl_add_u64 v[144:145], v[12:13], 0, v[8:9]
	s_mov_b32 m0, s22
	v_add_u32_e32 v12, 0x6000, v15
	v_lshl_add_u64 v[150:151], v[6:7], 0, v[8:9]
	v_add_u32_e32 v6, 0xe000, v15
	global_load_lds_dwordx4 v[144:145], off
	s_mov_b32 m0, s23
	v_readfirstlane_b32 s35, v12
	v_readfirstlane_b32 s44, v6
	v_lshrrev_b32_e32 v6, 5, v139
	v_bfe_u32 v153, v139, 1, 3
	s_add_i32 s17, 32, 0x10000
	global_load_lds_dwordx4 v[146:147], off
	v_lshl_add_u64 v[148:149], v[10:11], 0, v[8:9]
	s_mov_b32 m0, s35
	v_bitop3_b32 v6, v6, v153, 1 bitop3:0x6c
	v_add_u32_e32 v8, s17, v14
	global_load_lds_dwordx4 v[148:149], off
	s_mov_b32 m0, s44
	v_lshlrev_b32_e32 v166, 4, v6
	v_lshlrev_b32_e32 v6, 7, v139
	v_readfirstlane_b32 s1, v8
	v_add_u32_e32 v9, 0x8000, v8
	global_load_lds_dwordx4 v[150:151], off
	v_and_b32_e32 v167, 0x6f80, v6
	v_lshl_add_u64 v[6:7], v[0:1], 0, s[54:55]
	s_mov_b32 m0, s1
	v_readfirstlane_b32 s5, v9
	v_add_u32_e32 v9, 0x2000, v8
	global_load_lds_dwordx4 v[6:7], off
	v_lshl_add_u64 v[6:7], v[2:3], 0, s[54:55]
	s_mov_b32 m0, s5
	v_readfirstlane_b32 s6, v9
	v_add_u32_e32 v9, 0xa000, v8
	global_load_lds_dwordx4 v[6:7], off
	v_lshl_add_u64 v[6:7], v[134:135], 0, s[54:55]
	s_mov_b32 m0, s6
	v_readfirstlane_b32 s7, v9
	v_add_u32_e32 v9, 0x4000, v8
	global_load_lds_dwordx4 v[6:7], off
	v_lshl_add_u64 v[6:7], v[136:137], 0, s[54:55]
	s_mov_b32 m0, s7
	v_readfirstlane_b32 s13, v9
	v_add_u32_e32 v9, 0xc000, v8
	global_load_lds_dwordx4 v[6:7], off
	v_lshl_add_u64 v[6:7], v[144:145], 0, s[54:55]
	s_mov_b32 m0, s13
	v_readfirstlane_b32 s14, v9
	v_add_u32_e32 v9, 0x6000, v8
	global_load_lds_dwordx4 v[6:7], off
	v_lshl_add_u64 v[6:7], v[146:147], 0, s[54:55]
	s_mov_b32 m0, s14
	v_readfirstlane_b32 s15, v9
	v_add_u32_e32 v8, 0xe000, v8
	global_load_lds_dwordx4 v[6:7], off
	v_lshl_add_u64 v[6:7], v[148:149], 0, s[54:55]
	s_mov_b32 m0, s15
	v_readfirstlane_b32 s16, v8
	global_load_lds_dwordx4 v[6:7], off
	v_lshl_add_u64 v[6:7], v[150:151], 0, s[54:55]
	s_mov_b32 m0, s16
	v_add_u32_e32 v11, 32, v166
	global_load_lds_dwordx4 v[6:7], off
	v_add_u32_e32 v168, v11, v167
	v_and_b32_e32 v152, 31, v139
	v_lshrrev_b32_e32 v10, 1, v139
	s_waitcnt vmcnt(8)
	s_waitcnt lgkmcnt(0)
	s_barrier
	ds_read_b128 v[6:9], v168 offset:32768
	ds_read_b128 v[14:17], v168 offset:36864
	s_mov_b32 s45, 0x1ffff80
	v_and_or_b32 v10, v10, s45, v152
	v_lshlrev_b32_e32 v169, 7, v10
	v_add_u32_e32 v170, v11, v169
	ds_read_b128 v[10:13], v170
	s_waitcnt lgkmcnt(0)
	v_mfma_f32_32x32x16_bf16 v[118:133], v[6:9], v[10:13], 0
	v_bfe_u32 v171, v139, 5, 1
	s_mov_b32 m0, s18
	s_add_i32 s18, 32, 0x18000
	v_add3_u32 v179, s18, v166, v167
	v_add3_u32 v166, s17, v166, v169
	v_mfma_f32_32x32x16_bf16 v[102:117], v[14:17], v[10:13], 0
	ds_read_b128 v[10:13], v170 offset:4096
	s_waitcnt lgkmcnt(0)
	v_mfma_f32_32x32x16_bf16 v[86:101], v[6:9], v[10:13], 0
	v_mfma_f32_32x32x16_bf16 v[70:85], v[14:17], v[10:13], 0
	ds_read_b128 v[10:13], v170 offset:8192
	s_waitcnt lgkmcnt(0)
	v_mfma_f32_32x32x16_bf16 v[54:69], v[6:9], v[10:13], 0
	v_mfma_f32_32x32x16_bf16 v[38:53], v[14:17], v[10:13], 0
	ds_read_b128 v[10:13], v170 offset:12288
	s_waitcnt lgkmcnt(0)
	v_mfma_f32_32x32x16_bf16 v[22:37], v[6:9], v[10:13], 0
	v_bitop3_b32 v6, v171, v153, 2 bitop3:0x36
	v_lshlrev_b32_e32 v172, 4, v6
	v_add_u32_e32 v158, 32, v172
	v_add_u32_e32 v173, v158, v167
	ds_read_b128 v[154:157], v173 offset:32768
	ds_read_b128 v[162:165], v173 offset:36864
	v_add_u32_e32 v174, v158, v169
	ds_read_b128 v[158:161], v174
	s_waitcnt lgkmcnt(0)
	v_mfma_f32_32x32x16_bf16 v[118:133], v[154:157], v[158:161], v[118:133]
	v_add3_u32 v180, s18, v172, v167
	v_add3_u32 v172, s17, v172, v169
	v_mfma_f32_32x32x16_bf16 v[102:117], v[162:165], v[158:161], v[102:117]
	ds_read_b128 v[158:161], v174 offset:4096
	s_waitcnt lgkmcnt(0)
	v_mfma_f32_32x32x16_bf16 v[86:101], v[154:157], v[158:161], v[86:101]
	v_mfma_f32_32x32x16_bf16 v[70:85], v[162:165], v[158:161], v[70:85]
	ds_read_b128 v[158:161], v174 offset:8192
	v_mfma_f32_32x32x16_bf16 v[6:21], v[14:17], v[10:13], 0
	s_waitcnt lgkmcnt(0)
	v_mfma_f32_32x32x16_bf16 v[54:69], v[154:157], v[158:161], v[54:69]
	v_mfma_f32_32x32x16_bf16 v[38:53], v[162:165], v[158:161], v[38:53]
	ds_read_b128 v[158:161], v174 offset:12288
	s_waitcnt lgkmcnt(0)
	v_mfma_f32_32x32x16_bf16 v[22:37], v[154:157], v[158:161], v[22:37]
	v_bitop3_b32 v154, v171, v153, 4 bitop3:0x36
	v_lshlrev_b32_e32 v175, 4, v154
	v_bitop3_b32 v153, v171, v153, 6 bitop3:0x36
	v_lshlrev_b32_e32 v153, 4, v153
	v_add3_u32 v181, s18, v175, v167
	v_mfma_f32_32x32x16_bf16 v[6:21], v[162:165], v[158:161], v[6:21]
	v_add_u32_e32 v158, 32, v175
	v_add_u32_e32 v176, v158, v167
	ds_read_b128 v[154:157], v176 offset:32768
	ds_read_b128 v[162:165], v176 offset:36864
	v_add_u32_e32 v177, v158, v169
	ds_read_b128 v[158:161], v177
	v_add3_u32 v175, s17, v175, v169
	s_waitcnt lgkmcnt(0)
	v_mfma_f32_32x32x16_bf16 v[118:133], v[154:157], v[158:161], v[118:133]
	v_mfma_f32_32x32x16_bf16 v[102:117], v[162:165], v[158:161], v[102:117]
	ds_read_b128 v[158:161], v177 offset:4096
	s_waitcnt lgkmcnt(0)
	v_mfma_f32_32x32x16_bf16 v[86:101], v[154:157], v[158:161], v[86:101]
	v_mfma_f32_32x32x16_bf16 v[70:85], v[162:165], v[158:161], v[70:85]
	ds_read_b128 v[158:161], v177 offset:8192
	s_waitcnt lgkmcnt(0)
	v_mfma_f32_32x32x16_bf16 v[54:69], v[154:157], v[158:161], v[54:69]
	v_mfma_f32_32x32x16_bf16 v[38:53], v[162:165], v[158:161], v[38:53]
	ds_read_b128 v[158:161], v177 offset:12288
	s_waitcnt lgkmcnt(0)
	v_mfma_f32_32x32x16_bf16 v[22:37], v[154:157], v[158:161], v[22:37]
	v_mfma_f32_32x32x16_bf16 v[6:21], v[162:165], v[158:161], v[6:21]
	v_add_u32_e32 v158, 32, v153
	v_add_u32_e32 v171, v158, v167
	ds_read_b128 v[154:157], v171 offset:32768
	ds_read_b128 v[162:165], v171 offset:36864
	v_add_u32_e32 v178, v158, v169
	ds_read_b128 v[158:161], v178
	v_add3_u32 v167, s18, v153, v167
	s_waitcnt lgkmcnt(0)
	v_mfma_f32_32x32x16_bf16 v[118:133], v[154:157], v[158:161], v[118:133]
	v_add3_u32 v153, s17, v153, v169
	v_mfma_f32_32x32x16_bf16 v[102:117], v[162:165], v[158:161], v[102:117]
	ds_read_b128 v[158:161], v178 offset:4096
	s_waitcnt lgkmcnt(0)
	v_mfma_f32_32x32x16_bf16 v[86:101], v[154:157], v[158:161], v[86:101]
	v_mfma_f32_32x32x16_bf16 v[70:85], v[162:165], v[158:161], v[70:85]
	ds_read_b128 v[158:161], v178 offset:8192
	s_waitcnt lgkmcnt(0)
	v_mfma_f32_32x32x16_bf16 v[54:69], v[154:157], v[158:161], v[54:69]
	v_mfma_f32_32x32x16_bf16 v[38:53], v[162:165], v[158:161], v[38:53]
	ds_read_b128 v[158:161], v178 offset:12288
	s_waitcnt vmcnt(0)
	s_waitcnt vmcnt(0) lgkmcnt(0)
	s_barrier
	v_mfma_f32_32x32x16_bf16 v[22:37], v[154:157], v[158:161], v[22:37]
	v_lshl_add_u64 v[154:155], v[0:1], 0, s[96:97]
	global_load_lds_dwordx4 v[154:155], off
	v_lshl_add_u64 v[154:155], v[2:3], 0, s[96:97]
	s_mov_b32 m0, s19
	s_mov_b64 s[18:19], 0x180
	global_load_lds_dwordx4 v[154:155], off
	v_lshl_add_u64 v[154:155], v[134:135], 0, s[96:97]
	s_mov_b32 m0, s20
	v_mfma_f32_32x32x16_bf16 v[6:21], v[162:165], v[158:161], v[6:21]
	global_load_lds_dwordx4 v[154:155], off
	v_lshl_add_u64 v[154:155], v[136:137], 0, s[96:97]
	s_mov_b32 m0, s21
	v_lshl_add_u64 v[0:1], v[0:1], 0, s[18:19]
	global_load_lds_dwordx4 v[154:155], off
	v_lshl_add_u64 v[154:155], v[144:145], 0, s[96:97]
	s_mov_b32 m0, s22
	s_nop 0
	global_load_lds_dwordx4 v[154:155], off
	v_lshl_add_u64 v[154:155], v[146:147], 0, s[96:97]
	s_mov_b32 m0, s23
	s_nop 0
	global_load_lds_dwordx4 v[154:155], off
	v_lshl_add_u64 v[154:155], v[148:149], 0, s[96:97]
	s_mov_b32 m0, s35
	s_nop 0
	global_load_lds_dwordx4 v[154:155], off
	v_lshl_add_u64 v[154:155], v[150:151], 0, s[96:97]
	s_mov_b32 m0, s44
	s_nop 0
	global_load_lds_dwordx4 v[154:155], off
	ds_read_b128 v[154:157], v179
	ds_read_b128 v[158:161], v166
	ds_read_b128 v[162:165], v179 offset:4096
	s_waitcnt lgkmcnt(0)
	v_mfma_f32_32x32x16_bf16 v[118:133], v[154:157], v[158:161], v[118:133]
	s_mov_b32 m0, s1
	s_movk_i32 s1, 0x9f
	v_mfma_f32_32x32x16_bf16 v[102:117], v[162:165], v[158:161], v[102:117]
	ds_read_b128 v[158:161], v166 offset:4096
	s_waitcnt lgkmcnt(0)
	v_mfma_f32_32x32x16_bf16 v[86:101], v[154:157], v[158:161], v[86:101]
	v_mfma_f32_32x32x16_bf16 v[70:85], v[162:165], v[158:161], v[70:85]
	ds_read_b128 v[158:161], v166 offset:8192
	s_waitcnt lgkmcnt(0)
	v_mfma_f32_32x32x16_bf16 v[54:69], v[154:157], v[158:161], v[54:69]
	v_mfma_f32_32x32x16_bf16 v[38:53], v[162:165], v[158:161], v[38:53]
	ds_read_b128 v[158:161], v166 offset:12288
	s_waitcnt lgkmcnt(0)
	v_mfma_f32_32x32x16_bf16 v[22:37], v[154:157], v[158:161], v[22:37]
	ds_read_b128 v[154:157], v180
	v_mfma_f32_32x32x16_bf16 v[6:21], v[162:165], v[158:161], v[6:21]
	ds_read_b128 v[162:165], v180 offset:4096
	ds_read_b128 v[158:161], v172
	s_waitcnt lgkmcnt(0)
	v_mfma_f32_32x32x16_bf16 v[118:133], v[154:157], v[158:161], v[118:133]
	v_mfma_f32_32x32x16_bf16 v[102:117], v[162:165], v[158:161], v[102:117]
	ds_read_b128 v[158:161], v172 offset:4096
	s_waitcnt lgkmcnt(0)
	v_mfma_f32_32x32x16_bf16 v[86:101], v[154:157], v[158:161], v[86:101]
	v_mfma_f32_32x32x16_bf16 v[70:85], v[162:165], v[158:161], v[70:85]
	ds_read_b128 v[158:161], v172 offset:8192
	s_waitcnt lgkmcnt(0)
	v_mfma_f32_32x32x16_bf16 v[54:69], v[154:157], v[158:161], v[54:69]
	v_mfma_f32_32x32x16_bf16 v[38:53], v[162:165], v[158:161], v[38:53]
	ds_read_b128 v[158:161], v172 offset:12288
	s_waitcnt lgkmcnt(0)
	v_mfma_f32_32x32x16_bf16 v[22:37], v[154:157], v[158:161], v[22:37]
	ds_read_b128 v[154:157], v181
	v_mfma_f32_32x32x16_bf16 v[6:21], v[162:165], v[158:161], v[6:21]
	ds_read_b128 v[162:165], v181 offset:4096
	ds_read_b128 v[158:161], v175
	s_waitcnt lgkmcnt(0)
	v_mfma_f32_32x32x16_bf16 v[118:133], v[154:157], v[158:161], v[118:133]
	v_mfma_f32_32x32x16_bf16 v[102:117], v[162:165], v[158:161], v[102:117]
	ds_read_b128 v[158:161], v175 offset:4096
	s_waitcnt lgkmcnt(0)
	v_mfma_f32_32x32x16_bf16 v[86:101], v[154:157], v[158:161], v[86:101]
	v_mfma_f32_32x32x16_bf16 v[70:85], v[162:165], v[158:161], v[70:85]
	ds_read_b128 v[158:161], v175 offset:8192
	s_waitcnt lgkmcnt(0)
	v_mfma_f32_32x32x16_bf16 v[54:69], v[154:157], v[158:161], v[54:69]
	v_mfma_f32_32x32x16_bf16 v[38:53], v[162:165], v[158:161], v[38:53]
	ds_read_b128 v[158:161], v175 offset:12288
	s_waitcnt lgkmcnt(0)
	v_mfma_f32_32x32x16_bf16 v[22:37], v[154:157], v[158:161], v[22:37]
	ds_read_b128 v[154:157], v167
	v_mfma_f32_32x32x16_bf16 v[6:21], v[162:165], v[158:161], v[6:21]
	ds_read_b128 v[162:165], v167 offset:4096
	ds_read_b128 v[158:161], v153
	s_waitcnt lgkmcnt(0)
	v_mfma_f32_32x32x16_bf16 v[118:133], v[154:157], v[158:161], v[118:133]
	v_mfma_f32_32x32x16_bf16 v[102:117], v[162:165], v[158:161], v[102:117]
	ds_read_b128 v[158:161], v153 offset:4096
	s_waitcnt lgkmcnt(0)
	v_mfma_f32_32x32x16_bf16 v[86:101], v[154:157], v[158:161], v[86:101]
	v_mfma_f32_32x32x16_bf16 v[70:85], v[162:165], v[158:161], v[70:85]
	ds_read_b128 v[158:161], v153 offset:8192
	s_waitcnt lgkmcnt(0)
	v_mfma_f32_32x32x16_bf16 v[54:69], v[154:157], v[158:161], v[54:69]
	v_mfma_f32_32x32x16_bf16 v[38:53], v[162:165], v[158:161], v[38:53]
	ds_read_b128 v[158:161], v153 offset:12288
	s_waitcnt vmcnt(0)
	s_waitcnt vmcnt(0) lgkmcnt(0)
	s_barrier
	global_load_lds_dwordx4 v[0:1], off
	v_lshl_add_u64 v[0:1], v[2:3], 0, s[18:19]
	s_mov_b32 m0, s5
	v_mfma_f32_32x32x16_bf16 v[22:37], v[154:157], v[158:161], v[22:37]
	global_load_lds_dwordx4 v[0:1], off
	v_lshl_add_u64 v[0:1], v[134:135], 0, s[18:19]
	s_mov_b32 m0, s6
	s_nop 0
	global_load_lds_dwordx4 v[0:1], off
	v_lshl_add_u64 v[0:1], v[136:137], 0, s[18:19]
	s_mov_b32 m0, s7
	v_mfma_f32_32x32x16_bf16 v[6:21], v[162:165], v[158:161], v[6:21]
	global_load_lds_dwordx4 v[0:1], off
	v_lshl_add_u64 v[0:1], v[144:145], 0, s[18:19]
	s_mov_b32 m0, s13
	s_nop 0
	global_load_lds_dwordx4 v[0:1], off
	v_lshl_add_u64 v[0:1], v[146:147], 0, s[18:19]
	s_mov_b32 m0, s14
	s_nop 0
	global_load_lds_dwordx4 v[0:1], off
	v_lshl_add_u64 v[0:1], v[148:149], 0, s[18:19]
	s_mov_b32 m0, s15
	s_nop 0
	global_load_lds_dwordx4 v[0:1], off
	v_lshl_add_u64 v[0:1], v[150:151], 0, s[18:19]
	s_mov_b32 m0, s16
	s_nop 0
	global_load_lds_dwordx4 v[0:1], off
	ds_read_b128 v[0:3], v168 offset:32768
	ds_read_b128 v[134:137], v170
	ds_read_b128 v[144:147], v168 offset:36864
	s_waitcnt lgkmcnt(0)
	v_mfma_f32_32x32x16_bf16 v[118:133], v[0:3], v[134:137], v[118:133]
	v_mfma_f32_32x32x16_bf16 v[102:117], v[144:147], v[134:137], v[102:117]
	ds_read_b128 v[134:137], v170 offset:4096
	s_waitcnt lgkmcnt(0)
	v_mfma_f32_32x32x16_bf16 v[86:101], v[0:3], v[134:137], v[86:101]
	v_mfma_f32_32x32x16_bf16 v[70:85], v[144:147], v[134:137], v[70:85]
	ds_read_b128 v[134:137], v170 offset:8192
	s_waitcnt lgkmcnt(0)
	v_mfma_f32_32x32x16_bf16 v[54:69], v[0:3], v[134:137], v[54:69]
	v_mfma_f32_32x32x16_bf16 v[38:53], v[144:147], v[134:137], v[38:53]
	ds_read_b128 v[134:137], v170 offset:12288
	s_waitcnt lgkmcnt(0)
	v_mfma_f32_32x32x16_bf16 v[22:37], v[0:3], v[134:137], v[22:37]
	v_mfma_f32_32x32x16_bf16 v[6:21], v[144:147], v[134:137], v[6:21]
	ds_read_b128 v[0:3], v173 offset:32768
	ds_read_b128 v[134:137], v174
	ds_read_b128 v[144:147], v173 offset:36864
	s_waitcnt lgkmcnt(0)
	v_mfma_f32_32x32x16_bf16 v[118:133], v[0:3], v[134:137], v[118:133]
	v_mfma_f32_32x32x16_bf16 v[102:117], v[144:147], v[134:137], v[102:117]
	ds_read_b128 v[134:137], v174 offset:4096
	s_waitcnt lgkmcnt(0)
	v_mfma_f32_32x32x16_bf16 v[86:101], v[0:3], v[134:137], v[86:101]
	v_mfma_f32_32x32x16_bf16 v[70:85], v[144:147], v[134:137], v[70:85]
	ds_read_b128 v[134:137], v174 offset:8192
	s_waitcnt lgkmcnt(0)
	v_mfma_f32_32x32x16_bf16 v[54:69], v[0:3], v[134:137], v[54:69]
	v_mfma_f32_32x32x16_bf16 v[38:53], v[144:147], v[134:137], v[38:53]
	ds_read_b128 v[134:137], v174 offset:12288
	s_waitcnt lgkmcnt(0)
	v_mfma_f32_32x32x16_bf16 v[22:37], v[0:3], v[134:137], v[22:37]
	v_mfma_f32_32x32x16_bf16 v[6:21], v[144:147], v[134:137], v[6:21]
	ds_read_b128 v[0:3], v176 offset:32768
	ds_read_b128 v[134:137], v177
	ds_read_b128 v[144:147], v176 offset:36864
	s_waitcnt lgkmcnt(0)
	v_mfma_f32_32x32x16_bf16 v[118:133], v[0:3], v[134:137], v[118:133]
	v_mfma_f32_32x32x16_bf16 v[102:117], v[144:147], v[134:137], v[102:117]
	ds_read_b128 v[134:137], v177 offset:4096
	s_waitcnt lgkmcnt(0)
	v_mfma_f32_32x32x16_bf16 v[86:101], v[0:3], v[134:137], v[86:101]
	v_mfma_f32_32x32x16_bf16 v[70:85], v[144:147], v[134:137], v[70:85]
	ds_read_b128 v[134:137], v177 offset:8192
	s_waitcnt lgkmcnt(0)
	v_mfma_f32_32x32x16_bf16 v[54:69], v[0:3], v[134:137], v[54:69]
	v_mfma_f32_32x32x16_bf16 v[38:53], v[144:147], v[134:137], v[38:53]
	ds_read_b128 v[134:137], v177 offset:12288
	s_waitcnt lgkmcnt(0)
	v_mfma_f32_32x32x16_bf16 v[22:37], v[0:3], v[134:137], v[22:37]
	v_mfma_f32_32x32x16_bf16 v[6:21], v[144:147], v[134:137], v[6:21]
	ds_read_b128 v[0:3], v171 offset:32768
	ds_read_b128 v[134:137], v178
	ds_read_b128 v[144:147], v171 offset:36864
	s_waitcnt lgkmcnt(0)
	v_mfma_f32_32x32x16_bf16 v[118:133], v[0:3], v[134:137], v[118:133]
	v_mfma_f32_32x32x16_bf16 v[102:117], v[144:147], v[134:137], v[102:117]
	ds_read_b128 v[134:137], v178 offset:4096
	s_waitcnt lgkmcnt(0)
	v_mfma_f32_32x32x16_bf16 v[86:101], v[0:3], v[134:137], v[86:101]
	v_mfma_f32_32x32x16_bf16 v[70:85], v[144:147], v[134:137], v[70:85]
	ds_read_b128 v[134:137], v178 offset:8192
	s_waitcnt lgkmcnt(0)
	v_mfma_f32_32x32x16_bf16 v[54:69], v[0:3], v[134:137], v[54:69]
	v_mfma_f32_32x32x16_bf16 v[38:53], v[144:147], v[134:137], v[38:53]
	ds_read_b128 v[134:137], v178 offset:12288
	s_waitcnt vmcnt(0)
	s_waitcnt vmcnt(0) lgkmcnt(0)
	s_barrier
	v_mfma_f32_32x32x16_bf16 v[22:37], v[0:3], v[134:137], v[22:37]
	v_mfma_f32_32x32x16_bf16 v[6:21], v[144:147], v[134:137], v[6:21]
	ds_read_b128 v[0:3], v179
	ds_read_b128 v[134:137], v166
	ds_read_b128 v[144:147], v179 offset:4096
	s_waitcnt lgkmcnt(1)
	v_mfma_f32_32x32x16_bf16 v[118:133], v[0:3], v[134:137], v[118:133]
	s_waitcnt lgkmcnt(0)
	v_mfma_f32_32x32x16_bf16 v[102:117], v[144:147], v[134:137], v[102:117]
	ds_read_b128 v[134:137], v166 offset:4096
	s_waitcnt lgkmcnt(0)
	v_mfma_f32_32x32x16_bf16 v[86:101], v[0:3], v[134:137], v[86:101]
	v_mfma_f32_32x32x16_bf16 v[70:85], v[144:147], v[134:137], v[70:85]
	ds_read_b128 v[134:137], v166 offset:8192
	s_waitcnt lgkmcnt(0)
	v_mfma_f32_32x32x16_bf16 v[54:69], v[0:3], v[134:137], v[54:69]
	v_mfma_f32_32x32x16_bf16 v[38:53], v[144:147], v[134:137], v[38:53]
	ds_read_b128 v[134:137], v166 offset:12288
	s_waitcnt lgkmcnt(0)
	v_mfma_f32_32x32x16_bf16 v[22:37], v[0:3], v[134:137], v[22:37]
	v_mfma_f32_32x32x16_bf16 v[6:21], v[144:147], v[134:137], v[6:21]
	ds_read_b128 v[0:3], v180
	ds_read_b128 v[134:137], v172
	ds_read_b128 v[144:147], v180 offset:4096
	s_waitcnt lgkmcnt(1)
	v_mfma_f32_32x32x16_bf16 v[118:133], v[0:3], v[134:137], v[118:133]
	s_waitcnt lgkmcnt(0)
	v_mfma_f32_32x32x16_bf16 v[102:117], v[144:147], v[134:137], v[102:117]
	ds_read_b128 v[134:137], v172 offset:4096
	s_waitcnt lgkmcnt(0)
	v_mfma_f32_32x32x16_bf16 v[86:101], v[0:3], v[134:137], v[86:101]
	v_mfma_f32_32x32x16_bf16 v[70:85], v[144:147], v[134:137], v[70:85]
	ds_read_b128 v[134:137], v172 offset:8192
	s_waitcnt lgkmcnt(0)
	v_mfma_f32_32x32x16_bf16 v[54:69], v[0:3], v[134:137], v[54:69]
	v_mfma_f32_32x32x16_bf16 v[38:53], v[144:147], v[134:137], v[38:53]
	ds_read_b128 v[134:137], v172 offset:12288
	s_waitcnt lgkmcnt(0)
	v_mfma_f32_32x32x16_bf16 v[22:37], v[0:3], v[134:137], v[22:37]
	v_mfma_f32_32x32x16_bf16 v[6:21], v[144:147], v[134:137], v[6:21]
	ds_read_b128 v[0:3], v181
	ds_read_b128 v[134:137], v175
	ds_read_b128 v[144:147], v181 offset:4096
	s_waitcnt lgkmcnt(1)
	v_mfma_f32_32x32x16_bf16 v[118:133], v[0:3], v[134:137], v[118:133]
	s_waitcnt lgkmcnt(0)
	v_mfma_f32_32x32x16_bf16 v[102:117], v[144:147], v[134:137], v[102:117]
	ds_read_b128 v[134:137], v175 offset:4096
	s_waitcnt lgkmcnt(0)
	v_mfma_f32_32x32x16_bf16 v[86:101], v[0:3], v[134:137], v[86:101]
	v_mfma_f32_32x32x16_bf16 v[70:85], v[144:147], v[134:137], v[70:85]
	ds_read_b128 v[134:137], v175 offset:8192
	s_waitcnt lgkmcnt(0)
	v_mfma_f32_32x32x16_bf16 v[54:69], v[0:3], v[134:137], v[54:69]
	v_mfma_f32_32x32x16_bf16 v[38:53], v[144:147], v[134:137], v[38:53]
	ds_read_b128 v[134:137], v175 offset:12288
	s_waitcnt lgkmcnt(0)
	v_mfma_f32_32x32x16_bf16 v[22:37], v[0:3], v[134:137], v[22:37]
	v_mfma_f32_32x32x16_bf16 v[6:21], v[144:147], v[134:137], v[6:21]
	ds_read_b128 v[0:3], v167
	ds_read_b128 v[134:137], v153
	ds_read_b128 v[154:157], v167 offset:4096
	ds_read_b128 v[158:161], v153 offset:12288
	v_ashrrev_i32_e32 v144, 1, v139
	v_mov_b64_e32 v[146:147], 0xb152000
	s_waitcnt lgkmcnt(2)
	v_mfma_f32_32x32x16_bf16 v[118:133], v[0:3], v[134:137], v[118:133]
	s_waitcnt lgkmcnt(1)
	v_mfma_f32_32x32x16_bf16 v[102:117], v[154:157], v[134:137], v[102:117]
	ds_read_b128 v[134:137], v153 offset:4096
	s_waitcnt lgkmcnt(0)
	v_mfma_f32_32x32x16_bf16 v[86:101], v[0:3], v[134:137], v[86:101]
	v_mfma_f32_32x32x16_bf16 v[70:85], v[154:157], v[134:137], v[70:85]
	ds_read_b128 v[134:137], v153 offset:8192
	s_waitcnt vmcnt(0)
	s_waitcnt lgkmcnt(0)
	s_barrier
	v_mfma_f32_32x32x16_bf16 v[54:69], v[0:3], v[134:137], v[54:69]
	v_mfma_f32_32x32x16_bf16 v[38:53], v[154:157], v[134:137], v[38:53]
	v_and_b32_e32 v134, 0xffffff80, v144
	v_or_b32_e32 v135, v134, v152
	v_lshl_add_u32 v149, s4, 8, v135
	v_bitop3_b32 v136, v134, s1, v152 bitop3:0xc8
	v_ashrrev_i32_e32 v134, 5, v149
	v_and_b32_e32 v148, -8, v134
	v_cmp_lt_i32_e64 s[6:7], s89, v149
	v_mfma_f32_32x32x16_bf16 v[22:37], v[0:3], v[158:161], v[22:37]
	v_add_u32_e32 v0, 0xffffe000, v149
	v_lshrrev_b32_e32 v0, 9, v0
	v_mov_b64_e32 v[2:3], 8
	v_and_b32_e32 v137, 0xf9f, v149
	v_and_b32_e32 v150, 0x7ffff8, v0
	v_mov_b32_e32 v3, v148
	v_mov_b32_e32 v144, v136
	v_mfma_f32_32x32x16_bf16 v[6:21], v[154:157], v[158:161], v[6:21]
	s_and_saveexec_b64 s[4:5], s[6:7]
	v_mov_b64_e32 v[2:3], 12
	v_mov_b64_e32 v[146:147], 0xbd52000
	v_mov_b32_e32 v3, v150
	v_mov_b32_e32 v144, v137
	s_or_b64 exec, exec, s[4:5]
	v_and_b32_e32 v1, 0xc0, v139
	v_lshrrev_b32_e32 v0, 3, v139
	v_lshl_or_b32 v151, s0, 8, v1
	s_mov_b32 s0, 0x2aaaaaab
	v_and_b32_e32 v152, 4, v0
	v_mul_hi_i32 v0, v151, s0
	v_lshrrev_b32_e32 v1, 31, v0
	v_ashrrev_i32_e32 v0, 4, v0
	v_add_u32_e32 v139, v0, v1
	s_movk_i32 s0, 0x60
	v_mul_lo_u32 v0, v139, s0
	v_sub_u32_e32 v134, v151, v0
	v_cmp_eq_u32_e32 vcc, 64, v134
	s_and_b64 s[4:5], s[6:7], vcc
	v_lshlrev_b32_e32 v0, 2, v152
	s_and_saveexec_b64 s[0:1], s[4:5]
	s_cbranch_execz .LBB0_972
	v_readlane_b32 s4, v253, 31
	v_lshlrev_b32_e32 v154, 7, v144
	v_mov_b32_e32 v155, v4
	v_readlane_b32 s5, v253, 32
	v_mov_b32_e32 v1, v4
	s_nop 0
	v_lshl_add_u64 v[156:157], s[4:5], 0, v[154:155]
	v_readlane_b32 s4, v254, 47
	v_readlane_b32 s5, v254, 48
	v_lshl_add_u64 v[162:163], v[156:157], 0, v[0:1]
	s_nop 0
	v_lshl_add_u64 v[154:155], s[4:5], 0, v[154:155]
	v_lshl_add_u64 v[164:165], v[154:155], 0, v[0:1]
	global_load_dwordx4 v[154:157], v[162:163], off
	global_load_dwordx4 v[158:161], v[164:165], off
	s_waitcnt vmcnt(0)
	v_pk_mul_f32 v[166:167], v[122:123], v[158:159]
	s_nop 0
	v_pk_fma_f32 v[166:167], v[118:119], v[154:155], v[166:167] neg_lo:[0,0,1] neg_hi:[0,0,1]
	v_pk_mul_f32 v[118:119], v[118:119], v[158:159]
	s_nop 0
	v_pk_fma_f32 v[122:123], v[122:123], v[154:155], v[118:119]
	v_pk_mul_f32 v[118:119], v[124:125], v[160:161]
	s_nop 0
	v_pk_fma_f32 v[158:159], v[120:121], v[156:157], v[118:119] neg_lo:[0,0,1] neg_hi:[0,0,1]
	v_pk_mul_f32 v[118:119], v[120:121], v[160:161]
	s_nop 0
	v_pk_fma_f32 v[124:125], v[124:125], v[156:157], v[118:119]
	global_load_dwordx4 v[118:121], v[162:163], off offset:64
	global_load_dwordx4 v[154:157], v[164:165], off offset:64
	s_waitcnt vmcnt(0)
	v_pk_mul_f32 v[160:161], v[130:131], v[154:155]
	s_nop 0
	v_pk_fma_f32 v[160:161], v[126:127], v[118:119], v[160:161] neg_lo:[0,0,1] neg_hi:[0,0,1]
	v_pk_mul_f32 v[126:127], v[126:127], v[154:155]
	s_nop 0
	v_pk_fma_f32 v[130:131], v[130:131], v[118:119], v[126:127]
	v_pk_mul_f32 v[118:119], v[132:133], v[156:157]
	v_mov_b32_e32 v126, v160
	v_pk_fma_f32 v[154:155], v[128:129], v[120:121], v[118:119] neg_lo:[0,0,1] neg_hi:[0,0,1]
	v_pk_mul_f32 v[118:119], v[128:129], v[156:157]
	v_mov_b32_e32 v127, v161
	v_pk_fma_f32 v[132:133], v[132:133], v[120:121], v[118:119]
	v_mov_b32_e32 v118, v166
	v_mov_b32_e32 v119, v167
	v_mov_b32_e32 v120, v158
	v_mov_b32_e32 v121, v159
	v_mov_b32_e32 v128, v154
	v_mov_b32_e32 v129, v155
